# mLSTM chunk seg0: q/k causal conv + SiLU split across all 8 waves (threads 256..511 take tokens 4..7 of each 8-token group with their own prefetched rows), lower half keeps tokens 0..3
# baseline (speedup 1.0000x reference)
.LBB0_226:
	s_or_b64 exec, exec, s[60:61]
	v_or_b32_e32 v0, vcc_lo, v68
	v_mad_u64_u32 v[10:11], s[60:61], v0, s87, v[2:3]
	v_mad_i32_i24 v11, vcc_hi, v169, v11
	global_load_dwordx2 v[10:11], v[10:11], off
	v_mov_b32_e32 v0, v1
	v_mov_b32_e32 v2, v1
	v_mov_b32_e32 v3, v1
	v_mov_b64_e32 v[50:51], v[2:3]
	v_mov_b64_e32 v[48:49], v[0:1]
.LBB0_227:
	s_or_b64 exec, exec, s[46:47]
	v_lshlrev_b32_e32 v0, 1, v52
	v_lshl_add_u64 v[2:3], s[96:97], 0, v[0:1]
	v_or_b32_e32 v0, vcc_lo, v80
	v_mad_u64_u32 v[12:13], s[60:61], v0, s87, v[2:3]
	v_mad_i32_i24 v13, vcc_hi, v169, v13
	global_load_dwordx2 v[12:13], v[12:13], off
	v_or_b32_e32 v0, vcc_lo, v82
	v_mad_u64_u32 v[14:15], s[60:61], v0, s87, v[2:3]
	v_mad_i32_i24 v15, vcc_hi, v169, v15
	global_load_dwordx2 v[14:15], v[14:15], off
	v_or_b32_e32 v0, vcc_lo, v84
	v_mad_u64_u32 v[16:17], s[60:61], v0, s87, v[2:3]
	v_mad_i32_i24 v17, vcc_hi, v169, v17
	global_load_dwordx2 v[16:17], v[16:17], off
	v_or_b32_e32 v0, vcc_lo, v86
	v_mad_u64_u32 v[18:19], s[60:61], v0, s87, v[2:3]
	v_mad_i32_i24 v19, vcc_hi, v169, v19
	global_load_dwordx2 v[18:19], v[18:19], off
	v_or_b32_e32 v0, vcc_lo, v88
	v_mad_u64_u32 v[20:21], s[60:61], v0, s87, v[2:3]
	v_mad_i32_i24 v21, vcc_hi, v169, v21
	global_load_dwordx2 v[20:21], v[20:21], off
	v_or_b32_e32 v0, vcc_lo, v90
	v_mad_u64_u32 v[22:23], s[60:61], v0, s87, v[2:3]
	v_mad_i32_i24 v23, vcc_hi, v169, v23
	global_load_dwordx2 v[22:23], v[22:23], off
	v_or_b32_e32 v0, vcc_lo, v92
	v_mad_u64_u32 v[24:25], s[60:61], v0, s87, v[2:3]
	v_mad_i32_i24 v25, vcc_hi, v169, v25
	global_load_dwordx2 v[24:25], v[24:25], off
	v_mov_b32_e32 v0, v1
	v_mov_b64_e32 v[34:35], v[0:1]
	s_and_saveexec_b64 s[46:47], s[12:13]
	s_cbranch_execz .LBB0_229
	v_or_b32_e32 v0, vcc_lo, v64
	v_mov_b64_e32 v[2:3], s[96:97]
	v_mad_u64_u32 v[2:3], s[60:61], v0, s87, v[2:3]
	v_mad_i32_i24 v3, vcc_hi, v169, v3
	s_lshl_b32 s62, s59, 1
	v_lshl_add_u64 v[2:3], v[2:3], 0, s[62:63]
	v_add_co_u32_e32 v2, vcc, 0x2000, v2
	s_nop 1
	v_addc_co_u32_e32 v3, vcc, 0, v3, vcc
	global_load_ushort v35, v[2:3], off
	s_nop 0
	global_load_ushort v34, v[2:3], off offset:16

.LBB0_235:
	s_waitcnt vmcnt(0)
	v_lshlrev_b32_e32 v60, 16, v48
	v_and_b32_e32 v61, 0xffff0000, v48
	v_lshlrev_b32_e32 v62, 16, v49
	v_and_b32_e32 v63, 0xffff0000, v49
	v_lshlrev_b32_e32 v112, 16, v50
	v_and_b32_e32 v113, 0xffff0000, v50
	v_lshlrev_b32_e32 v114, 16, v51
	v_and_b32_e32 v115, 0xffff0000, v51
	ds_write_b128 v191, v[60:63] offset:32768
	ds_write_b128 v191, v[112:115] offset:32784
	v_lshlrev_b32_e32 v210, 16, v12
	v_and_b32_e32 v211, 0xffff0000, v12
	v_lshlrev_b32_e32 v212, 16, v13
	v_and_b32_e32 v213, 0xffff0000, v13
	v_lshlrev_b32_e32 v214, 16, v14
	v_and_b32_e32 v215, 0xffff0000, v14
	v_lshlrev_b32_e32 v216, 16, v15
	v_and_b32_e32 v217, 0xffff0000, v15
	v_lshlrev_b32_e32 v218, 16, v16
	v_and_b32_e32 v219, 0xffff0000, v16
	v_lshlrev_b32_e32 v220, 16, v17
	v_and_b32_e32 v221, 0xffff0000, v17
	v_lshlrev_b32_e32 v222, 16, v18
	v_and_b32_e32 v223, 0xffff0000, v18
	v_lshlrev_b32_e32 v224, 16, v19
	v_and_b32_e32 v225, 0xffff0000, v19
	v_lshlrev_b32_e32 v226, 16, v20
	v_and_b32_e32 v227, 0xffff0000, v20
	v_lshlrev_b32_e32 v228, 16, v21
	v_and_b32_e32 v229, 0xffff0000, v21
	v_lshlrev_b32_e32 v230, 16, v22
	v_and_b32_e32 v231, 0xffff0000, v22
	v_lshlrev_b32_e32 v232, 16, v23
	v_and_b32_e32 v233, 0xffff0000, v23
	v_lshlrev_b32_e32 v234, 16, v24
	v_and_b32_e32 v235, 0xffff0000, v24
	v_lshlrev_b32_e32 v236, 16, v25
	v_and_b32_e32 v237, 0xffff0000, v25
	v_pk_mul_f32 v[60:61], v[30:31], v[214:215]
	v_pk_fma_f32 v[60:61], v[26:27], v[210:211], v[60:61]
	v_pk_fma_f32 v[60:61], v[40:41], v[218:219], v[60:61]
	v_pk_fma_f32 v[60:61], v[44:45], v[222:223], v[60:61]
	v_pk_mul_f32 v[62:63], v[32:33], v[216:217]
	v_pk_fma_f32 v[62:63], v[28:29], v[212:213], v[62:63]
	v_pk_fma_f32 v[62:63], v[42:43], v[220:221], v[62:63]
	v_pk_fma_f32 v[62:63], v[46:47], v[224:225], v[62:63]
	v_mul_f32_e32 v112, 0xbfb8aa3b, v60
	v_mul_f32_e32 v113, 0xbfb8aa3b, v61
	v_mul_f32_e32 v114, 0xbfb8aa3b, v62
	v_mul_f32_e32 v115, 0xbfb8aa3b, v63
	v_exp_f32_e32 v112, v112
	v_exp_f32_e32 v113, v113
	v_exp_f32_e32 v114, v114
	v_exp_f32_e32 v115, v115
	v_add_f32_e32 v112, 1.0, v112
	v_add_f32_e32 v113, 1.0, v113
	v_add_f32_e32 v114, 1.0, v114
	v_add_f32_e32 v115, 1.0, v115
	v_rcp_f32_e32 v112, v112
	v_rcp_f32_e32 v113, v113
	v_rcp_f32_e32 v114, v114
	v_rcp_f32_e32 v115, v115
	v_pk_mul_f32 v[60:61], v[60:61], v[112:113]
	s_nop 0
	v_pk_mul_f32 v[62:63], v[62:63], v[114:115]
	v_pk_mul_f32 v[116:117], v[74:75], v[60:61]
	v_pk_mul_f32 v[118:119], v[94:95], v[62:63]
	ds_write_b128 v192, v[116:119] offset:1024
	v_pk_mul_f32 v[60:61], v[30:31], v[218:219]
	v_pk_fma_f32 v[60:61], v[26:27], v[214:215], v[60:61]
	v_pk_fma_f32 v[60:61], v[40:41], v[222:223], v[60:61]
	v_pk_fma_f32 v[60:61], v[44:45], v[226:227], v[60:61]
	v_pk_mul_f32 v[62:63], v[32:33], v[220:221]
	v_pk_fma_f32 v[62:63], v[28:29], v[216:217], v[62:63]
	v_pk_fma_f32 v[62:63], v[42:43], v[224:225], v[62:63]
	v_pk_fma_f32 v[62:63], v[46:47], v[228:229], v[62:63]
	v_mul_f32_e32 v112, 0xbfb8aa3b, v60
	v_mul_f32_e32 v113, 0xbfb8aa3b, v61
	v_mul_f32_e32 v114, 0xbfb8aa3b, v62
	v_mul_f32_e32 v115, 0xbfb8aa3b, v63
	v_exp_f32_e32 v112, v112
	v_exp_f32_e32 v113, v113
	v_exp_f32_e32 v114, v114
	v_exp_f32_e32 v115, v115
	v_add_f32_e32 v112, 1.0, v112
	v_add_f32_e32 v113, 1.0, v113
	v_add_f32_e32 v114, 1.0, v114
	v_add_f32_e32 v115, 1.0, v115
	v_rcp_f32_e32 v112, v112
	v_rcp_f32_e32 v113, v113
	v_rcp_f32_e32 v114, v114
	v_rcp_f32_e32 v115, v115
	v_pk_mul_f32 v[60:61], v[60:61], v[112:113]
	s_nop 0
	v_pk_mul_f32 v[62:63], v[62:63], v[114:115]
	v_pk_mul_f32 v[116:117], v[74:75], v[60:61]
	v_pk_mul_f32 v[118:119], v[94:95], v[62:63]
	ds_write_b128 v192, v[116:119] offset:1280
	v_pk_mul_f32 v[60:61], v[30:31], v[222:223]
	v_pk_fma_f32 v[60:61], v[26:27], v[218:219], v[60:61]
	v_pk_fma_f32 v[60:61], v[40:41], v[226:227], v[60:61]
	v_pk_fma_f32 v[60:61], v[44:45], v[230:231], v[60:61]
	v_pk_mul_f32 v[62:63], v[32:33], v[224:225]
	v_pk_fma_f32 v[62:63], v[28:29], v[220:221], v[62:63]
	v_pk_fma_f32 v[62:63], v[42:43], v[228:229], v[62:63]
	v_pk_fma_f32 v[62:63], v[46:47], v[232:233], v[62:63]
	v_mul_f32_e32 v112, 0xbfb8aa3b, v60
	v_mul_f32_e32 v113, 0xbfb8aa3b, v61
	v_mul_f32_e32 v114, 0xbfb8aa3b, v62
	v_mul_f32_e32 v115, 0xbfb8aa3b, v63
	v_exp_f32_e32 v112, v112
	v_exp_f32_e32 v113, v113
	v_exp_f32_e32 v114, v114
	v_exp_f32_e32 v115, v115
	v_add_f32_e32 v112, 1.0, v112
	v_add_f32_e32 v113, 1.0, v113
	v_add_f32_e32 v114, 1.0, v114
	v_add_f32_e32 v115, 1.0, v115
	v_rcp_f32_e32 v112, v112
	v_rcp_f32_e32 v113, v113
	v_rcp_f32_e32 v114, v114
	v_rcp_f32_e32 v115, v115
	v_pk_mul_f32 v[60:61], v[60:61], v[112:113]
	s_nop 0
	v_pk_mul_f32 v[62:63], v[62:63], v[114:115]
	v_pk_mul_f32 v[116:117], v[74:75], v[60:61]
	v_pk_mul_f32 v[118:119], v[94:95], v[62:63]
	ds_write_b128 v192, v[116:119] offset:1536
	v_pk_mul_f32 v[60:61], v[30:31], v[226:227]
	v_pk_fma_f32 v[60:61], v[26:27], v[222:223], v[60:61]
	v_pk_fma_f32 v[60:61], v[40:41], v[230:231], v[60:61]
	v_pk_fma_f32 v[60:61], v[44:45], v[234:235], v[60:61]
	v_pk_mul_f32 v[62:63], v[32:33], v[228:229]
	v_pk_fma_f32 v[62:63], v[28:29], v[224:225], v[62:63]
	v_pk_fma_f32 v[62:63], v[42:43], v[232:233], v[62:63]
	v_pk_fma_f32 v[62:63], v[46:47], v[236:237], v[62:63]
	v_mul_f32_e32 v112, 0xbfb8aa3b, v60
	v_mul_f32_e32 v113, 0xbfb8aa3b, v61
	v_mul_f32_e32 v114, 0xbfb8aa3b, v62
	v_mul_f32_e32 v115, 0xbfb8aa3b, v63
	v_exp_f32_e32 v112, v112
	v_exp_f32_e32 v113, v113
	v_exp_f32_e32 v114, v114
	v_exp_f32_e32 v115, v115
	v_add_f32_e32 v112, 1.0, v112
	v_add_f32_e32 v113, 1.0, v113
	v_add_f32_e32 v114, 1.0, v114
	v_add_f32_e32 v115, 1.0, v115
	v_rcp_f32_e32 v112, v112
	v_rcp_f32_e32 v113, v113
	v_rcp_f32_e32 v114, v114
	v_rcp_f32_e32 v115, v115
	v_pk_mul_f32 v[60:61], v[60:61], v[112:113]
	s_nop 0
	v_pk_mul_f32 v[62:63], v[62:63], v[114:115]
	v_pk_mul_f32 v[116:117], v[74:75], v[60:61]
	v_pk_mul_f32 v[118:119], v[94:95], v[62:63]
	ds_write_b128 v192, v[116:119] offset:1792
	s_andn2_saveexec_b64 vcc, s[46:47]
	s_cbranch_execz .LBB0_233
.LBB0_236:
	s_waitcnt vmcnt(10)
	v_lshlrev_b32_e32 v116, 16, v6
	v_and_b32_e32 v117, 0xffff0000, v6
	v_lshlrev_b32_e32 v62, 16, v4
	v_and_b32_e32 v63, 0xffff0000, v4
	s_waitcnt vmcnt(2)
	v_pk_mul_f32 v[114:115], v[30:31], v[116:117]
	v_lshlrev_b32_e32 v206, 16, v8
	v_and_b32_e32 v207, 0xffff0000, v8
	v_pk_fma_f32 v[62:63], v[26:27], v[62:63], v[114:115]
	v_lshlrev_b32_e32 v2, 16, v10
	v_and_b32_e32 v3, 0xffff0000, v10
	s_waitcnt vmcnt(1)
	v_pk_fma_f32 v[62:63], v[40:41], v[206:207], v[62:63]
	v_lshlrev_b32_e32 v118, 16, v7
	s_waitcnt vmcnt(0)
	v_pk_fma_f32 v[62:63], v[44:45], v[2:3], v[62:63]
	v_and_b32_e32 v119, 0xffff0000, v7
	v_mul_f32_e32 v0, 0xbfb8aa3b, v62
	v_exp_f32_e32 v0, v0
	v_lshlrev_b32_e32 v112, 16, v5
	v_and_b32_e32 v113, 0xffff0000, v5
	v_pk_mul_f32 v[120:121], v[32:33], v[118:119]
	v_add_f32_e32 v0, 1.0, v0
	v_rcp_f32_e32 v114, v0
	v_mul_f32_e32 v0, 0xbfb8aa3b, v63
	v_exp_f32_e32 v0, v0
	v_lshlrev_b32_e32 v208, 16, v9
	v_and_b32_e32 v209, 0xffff0000, v9
	v_pk_fma_f32 v[112:113], v[28:29], v[112:113], v[120:121]
	v_lshlrev_b32_e32 v60, 16, v11
	v_and_b32_e32 v61, 0xffff0000, v11
	v_pk_fma_f32 v[112:113], v[42:43], v[208:209], v[112:113]
	v_add_f32_e32 v0, 1.0, v0
	v_pk_fma_f32 v[112:113], v[46:47], v[60:61], v[112:113]
	v_rcp_f32_e32 v115, v0
	v_mul_f32_e32 v0, 0xbfb8aa3b, v112
	v_exp_f32_e32 v0, v0
	v_pk_mul_f32 v[62:63], v[62:63], v[114:115]
	v_add_f32_e32 v0, 1.0, v0
	v_rcp_f32_e32 v120, v0
	v_mul_f32_e32 v0, 0xbfb8aa3b, v113
	v_exp_f32_e32 v0, v0
	s_nop 0
	v_add_f32_e32 v0, 1.0, v0
	v_rcp_f32_e32 v121, v0
	s_nop 0
	v_pk_mul_f32 v[112:113], v[112:113], v[120:121]
	s_nop 0
	v_pk_mul_f32 v[114:115], v[94:95], v[112:113]
	v_pk_mul_f32 v[112:113], v[74:75], v[62:63]
	v_pk_mul_f32 v[62:63], v[30:31], v[206:207]
	ds_write_b128 v192, v[112:115]
	v_pk_fma_f32 v[62:63], v[26:27], v[116:117], v[62:63]
	v_lshlrev_b32_e32 v114, 16, v12
	v_and_b32_e32 v115, 0xffff0000, v12
	v_pk_fma_f32 v[62:63], v[40:41], v[2:3], v[62:63]
	v_pk_mul_f32 v[112:113], v[32:33], v[208:209]
	v_pk_fma_f32 v[62:63], v[44:45], v[114:115], v[62:63]
	v_pk_fma_f32 v[112:113], v[28:29], v[118:119], v[112:113]
	v_mul_f32_e32 v0, 0xbfb8aa3b, v62
	v_exp_f32_e32 v0, v0
	v_lshlrev_b32_e32 v120, 16, v13
	v_and_b32_e32 v121, 0xffff0000, v13
	v_pk_fma_f32 v[112:113], v[42:43], v[60:61], v[112:113]
	v_add_f32_e32 v0, 1.0, v0
	v_rcp_f32_e32 v116, v0
	v_mul_f32_e32 v0, 0xbfb8aa3b, v63
	v_exp_f32_e32 v0, v0
	v_pk_fma_f32 v[112:113], v[46:47], v[120:121], v[112:113]
	v_add_f32_e32 v0, 1.0, v0
	v_rcp_f32_e32 v117, v0
	v_mul_f32_e32 v0, 0xbfb8aa3b, v112
	v_exp_f32_e32 v0, v0
	v_pk_mul_f32 v[62:63], v[62:63], v[116:117]
	s_nop 0
	v_pk_mul_f32 v[116:117], v[74:75], v[62:63]
	v_add_f32_e32 v0, 1.0, v0
	v_rcp_f32_e32 v118, v0
	v_mul_f32_e32 v0, 0xbfb8aa3b, v113
	v_exp_f32_e32 v0, v0
	v_pk_mul_f32 v[62:63], v[30:31], v[2:3]
	v_add_f32_e32 v0, 1.0, v0
	v_rcp_f32_e32 v119, v0
	v_pk_fma_f32 v[62:63], v[26:27], v[206:207], v[62:63]
	v_pk_mul_f32 v[112:113], v[112:113], v[118:119]
	s_nop 0
	v_pk_mul_f32 v[118:119], v[94:95], v[112:113]
	v_lshlrev_b32_e32 v112, 16, v14
	v_and_b32_e32 v113, 0xffff0000, v14
	v_pk_fma_f32 v[62:63], v[40:41], v[114:115], v[62:63]
	ds_write_b128 v192, v[116:119] offset:256
	v_pk_fma_f32 v[62:63], v[44:45], v[112:113], v[62:63]
	v_pk_mul_f32 v[116:117], v[32:33], v[60:61]
	v_mul_f32_e32 v0, 0xbfb8aa3b, v62
	v_exp_f32_e32 v0, v0
	v_pk_fma_f32 v[116:117], v[28:29], v[208:209], v[116:117]
	v_lshlrev_b32_e32 v118, 16, v15
	v_and_b32_e32 v119, 0xffff0000, v15
	v_add_f32_e32 v0, 1.0, v0
	v_rcp_f32_e32 v206, v0
	v_mul_f32_e32 v0, 0xbfb8aa3b, v63
	v_exp_f32_e32 v0, v0
	v_pk_fma_f32 v[116:117], v[42:43], v[120:121], v[116:117]
	v_add_f32_e32 v0, 1.0, v0
	v_pk_fma_f32 v[116:117], v[46:47], v[118:119], v[116:117]
	v_rcp_f32_e32 v207, v0
	v_mul_f32_e32 v0, 0xbfb8aa3b, v116
	v_exp_f32_e32 v0, v0
	v_pk_mul_f32 v[62:63], v[62:63], v[206:207]
	s_nop 0
	v_pk_mul_f32 v[206:207], v[74:75], v[62:63]
	v_add_f32_e32 v0, 1.0, v0
	v_rcp_f32_e32 v208, v0
	v_mul_f32_e32 v0, 0xbfb8aa3b, v117
	v_exp_f32_e32 v0, v0
	v_lshlrev_b32_e32 v62, 16, v16
	v_and_b32_e32 v63, 0xffff0000, v16
	v_add_f32_e32 v0, 1.0, v0
	v_rcp_f32_e32 v209, v0
	s_nop 0
	v_pk_mul_f32 v[116:117], v[116:117], v[208:209]
	s_nop 0
	v_pk_mul_f32 v[208:209], v[94:95], v[116:117]
	ds_write_b128 v192, v[206:209] offset:512
	v_pk_mul_f32 v[206:207], v[30:31], v[114:115]
	v_pk_mul_f32 v[208:209], v[32:33], v[120:121]
	v_pk_fma_f32 v[2:3], v[26:27], v[2:3], v[206:207]
	v_pk_fma_f32 v[60:61], v[28:29], v[60:61], v[208:209]
	v_pk_fma_f32 v[2:3], v[40:41], v[112:113], v[2:3]
	v_lshlrev_b32_e32 v116, 16, v17
	v_pk_fma_f32 v[2:3], v[44:45], v[62:63], v[2:3]
	v_and_b32_e32 v117, 0xffff0000, v17
	v_mul_f32_e32 v0, 0xbfb8aa3b, v2
	v_exp_f32_e32 v0, v0
	v_pk_fma_f32 v[60:61], v[42:43], v[118:119], v[60:61]
	v_add_f32_e32 v0, 1.0, v0
	v_rcp_f32_e32 v206, v0
	v_mul_f32_e32 v0, 0xbfb8aa3b, v3
	v_exp_f32_e32 v0, v0
	v_pk_fma_f32 v[60:61], v[46:47], v[116:117], v[60:61]
	v_add_f32_e32 v0, 1.0, v0
	v_rcp_f32_e32 v207, v0
	v_mul_f32_e32 v0, 0xbfb8aa3b, v60
	v_exp_f32_e32 v0, v0
	v_pk_mul_f32 v[2:3], v[2:3], v[206:207]
	s_nop 0
	v_pk_mul_f32 v[206:207], v[74:75], v[2:3]
	v_add_f32_e32 v0, 1.0, v0
	v_rcp_f32_e32 v208, v0
	v_mul_f32_e32 v0, 0xbfb8aa3b, v61
	v_exp_f32_e32 v0, v0
	v_lshlrev_b32_e32 v2, 16, v18
	v_and_b32_e32 v3, 0xffff0000, v18
	v_add_f32_e32 v0, 1.0, v0
	v_rcp_f32_e32 v209, v0
	s_nop 0
	v_pk_mul_f32 v[60:61], v[60:61], v[208:209]
	s_nop 0
	v_pk_mul_f32 v[208:209], v[94:95], v[60:61]
	ds_write_b128 v192, v[206:209] offset:768
	s_or_b64 exec, exec, vcc
	s_and_saveexec_b64 s[46:47], s[12:13]
	s_cbranch_execz .LBB0_234

.LBB0_242:
	s_or_b64 exec, exec, s[46:47]
	v_lshl_add_u64 v[2:3], v[106:107], 0, s[76:77]
	s_mov_b32 s61, 0
	s_mov_b32 s60, 0x808a200
	v_lshl_add_u64 v[12:13], v[2:3], 0, s[60:61]
	global_load_dwordx2 v[12:13], v[12:13], off
	s_mov_b32 s60, 0x808c400
	v_lshl_add_u64 v[14:15], v[2:3], 0, s[60:61]
	global_load_dwordx2 v[14:15], v[14:15], off
	s_mov_b32 s60, 0x808e600
	v_lshl_add_u64 v[16:17], v[2:3], 0, s[60:61]
	global_load_dwordx2 v[16:17], v[16:17], off
	s_mov_b32 s60, 0x8090800
	v_lshl_add_u64 v[18:19], v[2:3], 0, s[60:61]
	global_load_dwordx2 v[18:19], v[18:19], off
	s_mov_b32 s60, 0x8092a00
	v_lshl_add_u64 v[20:21], v[2:3], 0, s[60:61]
	global_load_dwordx2 v[20:21], v[20:21], off
	s_mov_b32 s60, 0x8094c00
	v_lshl_add_u64 v[22:23], v[2:3], 0, s[60:61]
	global_load_dwordx2 v[22:23], v[22:23], off
	s_mov_b32 s60, 0x8096e00
	v_lshl_add_u64 v[24:25], v[2:3], 0, s[60:61]
	global_load_dwordx2 v[24:25], v[24:25], off
	s_and_saveexec_b64 s[46:47], s[12:13]
	s_cbranch_execz .LBB0_244

.LBB0_274:
	v_lshl_add_u64 v[2:3], v[106:107], 0, s[76:77]
	s_mov_b32 s61, 0
	s_mov_b32 s60, 0x8081a00
	v_lshl_add_u64 v[4:5], v[2:3], 0, s[60:61]
	global_load_dwordx2 v[4:5], v[4:5], off
	s_mov_b32 s60, 0x8083c00
	v_lshl_add_u64 v[6:7], v[2:3], 0, s[60:61]
	global_load_dwordx2 v[6:7], v[6:7], off
	s_mov_b32 s60, 0x8085e00
	v_lshl_add_u64 v[8:9], v[2:3], 0, s[60:61]
	global_load_dwordx2 v[8:9], v[8:9], off
	s_mov_b32 s60, 0x8088000
	v_lshl_add_u64 v[10:11], v[2:3], 0, s[60:61]
	global_load_dwordx2 v[10:11], v[10:11], off
	s_branch .LBB0_242
